# phase 9: ACT tile through wave-private LDS transpose, 4 row-contiguous stores per wave instead of 16 scattered
# baseline (speedup 1.0000x reference)
.LBB0_2262:
	s_lshl_b32 s6, s5, 7
	s_ashr_i32 s7, s6, 31
	s_lshl_b64 s[8:9], s[6:7], 11
	v_mov_b32_e32 v0, v161
	s_add_u32 s8, s12, s8
	s_waitcnt vmcnt(8)
	v_mov_b32_e32 v49, v186
	s_addc_u32 s9, s13, s9
	s_ashr_i32 s5, s4, 31
	s_lshl_b64 s[10:11], s[4:5], 18
	v_lshlrev_b32_e32 v16, 4, v49
	v_ashrrev_i32_e32 v50, 3, v49
	v_and_b32_e32 v48, 0x70, v16
	s_add_u32 s10, s14, s10
	v_lshl_or_b32 v168, v50, 11, v48
	s_addc_u32 s11, s15, s11
	v_add_u32_e32 v169, 0x10000, v168
	v_add_u32_e32 v170, 0x20000, v168
	v_add_u32_e32 v171, 0x30000, v168
	s_barrier
	s_lshl_b32 s72, s6, 5
	s_add_u32 s72, s72, 0xec00000
	s_add_u32 s72, s88, s72
	s_addc_u32 s73, s89, 0
	global_load_dwordx4 v[222:225], v248, s[72:73]
	global_load_dwordx4 v[226:229], v248, s[72:73] offset:16
	global_load_dwordx4 v[136:139], v248, s[72:73] offset:1024
	global_load_dwordx4 v[140:143], v248, s[72:73] offset:1040
	global_load_dwordx4 v[16:19], v168, s[8:9]
	global_load_dwordx4 v[20:23], v169, s[8:9]
	global_load_dwordx4 v[24:27], v170, s[8:9]
	global_load_dwordx4 v[28:31], v171, s[8:9]
	global_load_dwordx4 v[32:35], v168, s[10:11]
	global_load_dwordx4 v[36:39], v169, s[10:11]
	global_load_dwordx4 v[40:43], v170, s[10:11]
	global_load_dwordx4 v[44:47], v171, s[10:11]
	v_mad_u64_u32 v[130:131], s[18:19], v50, s43, v[48:49]
	v_mov_b32_e32 v1, v0
	v_mov_b32_e32 v2, v0
	v_mov_b32_e32 v3, v0
	v_mov_b32_e32 v4, v0
	v_mov_b32_e32 v5, v0
	v_mov_b32_e32 v6, v0
	v_mov_b32_e32 v7, v0
	s_waitcnt vmcnt(8)
	v_mov_b32_e32 v8, v0
	v_mov_b32_e32 v9, v0
	v_mov_b32_e32 v10, v0
	v_mov_b32_e32 v11, v0
	v_mov_b32_e32 v12, v0
	v_mov_b32_e32 v13, v0
	v_mov_b32_e32 v14, v0
	v_mov_b32_e32 v15, v0
	s_waitcnt vmcnt(7)
	ds_write_b128 v130, v[16:19]
	s_waitcnt vmcnt(6)
	ds_write_b128 v130, v[20:23] offset:4608
	s_waitcnt vmcnt(5)
	ds_write_b128 v130, v[24:27] offset:9216
	s_waitcnt vmcnt(4)
	ds_write_b128 v130, v[28:31] offset:13824
	s_waitcnt vmcnt(3)
	ds_write_b128 v130, v[32:35] offset:36864
	s_waitcnt vmcnt(2)
	ds_write_b128 v130, v[36:39] offset:41472
	s_waitcnt vmcnt(1)
	ds_write_b128 v130, v[40:43] offset:46080
	s_waitcnt vmcnt(0)
	ds_write_b128 v130, v[44:47] offset:50688
	global_load_dwordx4 v[96:99], v168, s[8:9] offset:128
	global_load_dwordx4 v[100:103], v169, s[8:9] offset:128
	global_load_dwordx4 v[104:107], v170, s[8:9] offset:128
	global_load_dwordx4 v[108:111], v171, s[8:9] offset:128
	global_load_dwordx4 v[64:67], v168, s[10:11] offset:128
	global_load_dwordx4 v[68:71], v169, s[10:11] offset:128
	global_load_dwordx4 v[72:75], v170, s[10:11] offset:128
	global_load_dwordx4 v[76:79], v171, s[10:11] offset:128
	v_lshrrev_b32_e32 v18, 1, v49
	v_and_b32_e32 v17, 0x5f, v49
	v_and_b32_e32 v16, 16, v18
	v_mad_u32_u24 v131, v17, s43, v16
	v_and_b32_e32 v17, 31, v49
	v_and_or_b32 v17, v18, s44, v17
	v_mad_u64_u32 v[128:129], s[18:19], v17, s43, v[16:17]
	s_waitcnt lgkmcnt(0)
	s_barrier
	ds_read_b128 v[16:19], v128
	ds_read_b128 v[84:87], v131 offset:41472
	ds_read_b128 v[80:83], v128 offset:4608
	ds_read_b128 v[172:175], v128 offset:32
	s_waitcnt lgkmcnt(2)
	v_mfma_f32_32x32x16_bf16 v[48:63], v[84:87], v[16:19], v[0:15]
	ds_read_b128 v[88:91], v131 offset:36864
	ds_read_b128 v[176:179], v128 offset:4640
	ds_read_b128 v[180:183], v131 offset:36896
	ds_read_b128 v[196:199], v131 offset:41504
	v_add_u32_e32 v129, 0xd800, v130
	s_waitcnt lgkmcnt(3)
	v_mfma_f32_32x32x16_bf16 v[32:47], v[88:91], v[16:19], v[0:15]
	v_mfma_f32_32x32x16_bf16 v[16:31], v[88:91], v[80:83], v[0:15]
	v_mfma_f32_32x32x16_bf16 v[0:15], v[84:87], v[80:83], v[0:15]
	s_waitcnt lgkmcnt(1)
	v_mfma_f32_32x32x16_bf16 v[32:47], v[180:183], v[172:175], v[32:47]
	s_waitcnt lgkmcnt(0)
	v_mfma_f32_32x32x16_bf16 v[48:63], v[196:199], v[172:175], v[48:63]
	v_mfma_f32_32x32x16_bf16 v[16:31], v[180:183], v[176:179], v[16:31]
	v_mfma_f32_32x32x16_bf16 v[0:15], v[196:199], v[176:179], v[0:15]
	ds_read_b128 v[200:203], v128 offset:64
	ds_read_b128 v[210:213], v128 offset:4672
	ds_read_b128 v[214:217], v131 offset:36928
	ds_read_b128 v[218:221], v131 offset:41536
	s_waitcnt lgkmcnt(1)
	v_mfma_f32_32x32x16_bf16 v[32:47], v[214:217], v[200:203], v[32:47]
	s_waitcnt lgkmcnt(0)
	v_mfma_f32_32x32x16_bf16 v[48:63], v[218:221], v[200:203], v[48:63]
	v_mfma_f32_32x32x16_bf16 v[16:31], v[214:217], v[210:213], v[16:31]
	v_mfma_f32_32x32x16_bf16 v[0:15], v[218:221], v[210:213], v[0:15]
	global_load_dwordx4 v[112:115], v168, s[8:9] offset:256
	global_load_dwordx4 v[116:119], v169, s[8:9] offset:256
	global_load_dwordx4 v[120:123], v170, s[8:9] offset:256
	global_load_dwordx4 v[124:127], v171, s[8:9] offset:256
	global_load_dwordx4 v[80:83], v168, s[10:11] offset:256
	global_load_dwordx4 v[84:87], v169, s[10:11] offset:256
	global_load_dwordx4 v[88:91], v170, s[10:11] offset:256
	global_load_dwordx4 v[92:95], v171, s[10:11] offset:256
	s_waitcnt vmcnt(15)
	ds_write_b128 v130, v[96:99] offset:18432
	s_waitcnt vmcnt(14)
	ds_write_b128 v130, v[100:103] offset:23040
	s_waitcnt vmcnt(13)
	ds_write_b128 v130, v[104:107] offset:27648
	s_waitcnt vmcnt(12)
	ds_write_b128 v130, v[108:111] offset:32256
	ds_read_b128 v[96:99], v128 offset:96
	ds_read_b128 v[100:103], v128 offset:4704
	ds_read_b128 v[104:107], v131 offset:36960
	ds_read_b128 v[108:111], v131 offset:41568
	s_waitcnt vmcnt(11)
	ds_write_b128 v130, v[64:67] offset:55296
	s_waitcnt vmcnt(10)
	ds_write_b128 v130, v[68:71] offset:59904
	s_waitcnt vmcnt(9)
	ds_write_b128 v130, v[72:75] offset:64512
	s_waitcnt vmcnt(8)
	ds_write_b128 v129, v[76:79] offset:13824
	s_waitcnt lgkmcnt(5)
	v_mfma_f32_32x32x16_bf16 v[32:47], v[104:107], v[96:99], v[32:47]
	s_waitcnt lgkmcnt(0)
	s_barrier
	v_mfma_f32_32x32x16_bf16 v[48:63], v[108:111], v[96:99], v[48:63]
	v_mfma_f32_32x32x16_bf16 v[16:31], v[104:107], v[100:103], v[16:31]
	v_mfma_f32_32x32x16_bf16 v[0:15], v[108:111], v[100:103], v[0:15]
	ds_read_b128 v[64:67], v128 offset:23040
	ds_read_b128 v[72:75], v128 offset:18432
	ds_read_b128 v[68:71], v131 offset:59904
	ds_read_b128 v[100:103], v131 offset:55296
	ds_read_b128 v[76:79], v128 offset:18464
	ds_read_b128 v[96:99], v128 offset:23072
	ds_read_b128 v[104:107], v131 offset:55328
	ds_read_b128 v[108:111], v131 offset:59936
	s_waitcnt lgkmcnt(4)
	v_mfma_f32_32x32x16_bf16 v[32:47], v[100:103], v[72:75], v[32:47]
	v_mfma_f32_32x32x16_bf16 v[48:63], v[68:71], v[72:75], v[48:63]
	v_mfma_f32_32x32x16_bf16 v[16:31], v[100:103], v[64:67], v[16:31]
	v_mfma_f32_32x32x16_bf16 v[0:15], v[68:71], v[64:67], v[0:15]
	global_load_dwordx4 v[64:67], v168, s[8:9] offset:384
	global_load_dwordx4 v[68:71], v169, s[8:9] offset:384
	global_load_dwordx4 v[72:75], v170, s[8:9] offset:384
	global_load_dwordx4 v[100:103], v171, s[8:9] offset:384
	global_load_dwordx4 v[172:175], v168, s[10:11] offset:384
	global_load_dwordx4 v[176:179], v169, s[10:11] offset:384
	global_load_dwordx4 v[180:183], v170, s[10:11] offset:384
	global_load_dwordx4 v[196:199], v171, s[10:11] offset:384
	ds_read_b128 v[200:203], v128 offset:18496
	ds_read_b128 v[210:213], v128 offset:23104
	ds_read_b128 v[214:217], v131 offset:55360
	ds_read_b128 v[218:221], v131 offset:59968
	s_waitcnt vmcnt(15)
	ds_write_b128 v130, v[112:115]
	s_waitcnt vmcnt(14)
	ds_write_b128 v130, v[116:119] offset:4608
	s_waitcnt vmcnt(13)
	ds_write_b128 v130, v[120:123] offset:9216
	s_waitcnt vmcnt(12)
	ds_write_b128 v130, v[124:127] offset:13824
	s_waitcnt lgkmcnt(9)
	v_mfma_f32_32x32x16_bf16 v[32:47], v[104:107], v[76:79], v[32:47]
	s_waitcnt lgkmcnt(8)
	v_mfma_f32_32x32x16_bf16 v[48:63], v[108:111], v[76:79], v[48:63]
	v_mfma_f32_32x32x16_bf16 v[16:31], v[104:107], v[96:99], v[16:31]
	v_mfma_f32_32x32x16_bf16 v[0:15], v[108:111], v[96:99], v[0:15]
	ds_read_b128 v[76:79], v128 offset:18528
	ds_read_b128 v[96:99], v128 offset:23136
	ds_read_b128 v[104:107], v131 offset:55392
	ds_read_b128 v[108:111], v131 offset:60000
	s_waitcnt vmcnt(11)
	ds_write_b128 v130, v[80:83] offset:36864
	s_waitcnt vmcnt(10)
	ds_write_b128 v130, v[84:87] offset:41472
	s_waitcnt vmcnt(9)
	ds_write_b128 v130, v[88:91] offset:46080
	s_waitcnt vmcnt(8)
	ds_write_b128 v130, v[92:95] offset:50688
	s_waitcnt lgkmcnt(13)
	v_mfma_f32_32x32x16_bf16 v[32:47], v[214:217], v[200:203], v[32:47]
	s_waitcnt lgkmcnt(0)
	s_barrier
	v_mfma_f32_32x32x16_bf16 v[48:63], v[218:221], v[200:203], v[48:63]
	v_mfma_f32_32x32x16_bf16 v[16:31], v[214:217], v[210:213], v[16:31]
	v_mfma_f32_32x32x16_bf16 v[0:15], v[218:221], v[210:213], v[0:15]
	v_mfma_f32_32x32x16_bf16 v[32:47], v[104:107], v[76:79], v[32:47]
	v_mfma_f32_32x32x16_bf16 v[48:63], v[108:111], v[76:79], v[48:63]
	v_mfma_f32_32x32x16_bf16 v[16:31], v[104:107], v[96:99], v[16:31]
	v_mfma_f32_32x32x16_bf16 v[0:15], v[108:111], v[96:99], v[0:15]
	ds_read_b128 v[76:79], v128 offset:4608
	ds_read_b128 v[84:87], v128
	ds_read_b128 v[80:83], v131 offset:41472
	ds_read_b128 v[96:99], v131 offset:36864
	ds_read_b128 v[88:91], v128 offset:32
	ds_read_b128 v[92:95], v128 offset:4640
	ds_read_b128 v[104:107], v131 offset:36896
	ds_read_b128 v[108:111], v131 offset:41504
	s_waitcnt lgkmcnt(4)
	v_mfma_f32_32x32x16_bf16 v[32:47], v[96:99], v[84:87], v[32:47]
	v_mfma_f32_32x32x16_bf16 v[48:63], v[80:83], v[84:87], v[48:63]
	v_mfma_f32_32x32x16_bf16 v[16:31], v[96:99], v[76:79], v[16:31]
	v_mfma_f32_32x32x16_bf16 v[0:15], v[80:83], v[76:79], v[0:15]
	global_load_dwordx4 v[76:79], v168, s[8:9] offset:512
	global_load_dwordx4 v[80:83], v169, s[8:9] offset:512
	global_load_dwordx4 v[84:87], v170, s[8:9] offset:512
	global_load_dwordx4 v[96:99], v171, s[8:9] offset:512
	global_load_dwordx4 v[112:115], v168, s[10:11] offset:512
	global_load_dwordx4 v[116:119], v169, s[10:11] offset:512
	global_load_dwordx4 v[120:123], v170, s[10:11] offset:512
	global_load_dwordx4 v[124:127], v171, s[10:11] offset:512
	ds_read_b128 v[200:203], v128 offset:64
	ds_read_b128 v[210:213], v128 offset:4672
	ds_read_b128 v[214:217], v131 offset:36928
	ds_read_b128 v[218:221], v131 offset:41536
	s_waitcnt vmcnt(15)
	ds_write_b128 v130, v[64:67] offset:18432
	s_waitcnt vmcnt(14)
	ds_write_b128 v130, v[68:71] offset:23040
	s_waitcnt vmcnt(13)
	ds_write_b128 v130, v[72:75] offset:27648
	s_waitcnt vmcnt(12)
	ds_write_b128 v130, v[100:103] offset:32256
	s_waitcnt lgkmcnt(9)
	v_mfma_f32_32x32x16_bf16 v[32:47], v[104:107], v[88:91], v[32:47]
	s_waitcnt lgkmcnt(8)
	v_mfma_f32_32x32x16_bf16 v[48:63], v[108:111], v[88:91], v[48:63]
	v_mfma_f32_32x32x16_bf16 v[16:31], v[104:107], v[92:95], v[16:31]
	v_mfma_f32_32x32x16_bf16 v[0:15], v[108:111], v[92:95], v[0:15]
	ds_read_b128 v[64:67], v128 offset:96
	ds_read_b128 v[68:71], v128 offset:4704
	ds_read_b128 v[72:75], v131 offset:36960
	ds_read_b128 v[88:91], v131 offset:41568
	s_waitcnt vmcnt(11)
	ds_write_b128 v130, v[172:175] offset:55296
	s_waitcnt vmcnt(10)
	ds_write_b128 v130, v[176:179] offset:59904
	s_waitcnt vmcnt(9)
	ds_write_b128 v130, v[180:183] offset:64512
	s_waitcnt vmcnt(8)
	ds_write_b128 v129, v[196:199] offset:13824
	s_waitcnt lgkmcnt(13)
	v_mfma_f32_32x32x16_bf16 v[32:47], v[214:217], v[200:203], v[32:47]
	s_waitcnt lgkmcnt(0)
	s_barrier
	v_mfma_f32_32x32x16_bf16 v[48:63], v[218:221], v[200:203], v[48:63]
	v_mfma_f32_32x32x16_bf16 v[16:31], v[214:217], v[210:213], v[16:31]
	v_mfma_f32_32x32x16_bf16 v[0:15], v[218:221], v[210:213], v[0:15]
	v_mfma_f32_32x32x16_bf16 v[32:47], v[72:75], v[64:67], v[32:47]
	v_mfma_f32_32x32x16_bf16 v[48:63], v[88:91], v[64:67], v[48:63]
	v_mfma_f32_32x32x16_bf16 v[16:31], v[72:75], v[68:71], v[16:31]
	v_mfma_f32_32x32x16_bf16 v[0:15], v[88:91], v[68:71], v[0:15]
	ds_read_b128 v[64:67], v128 offset:23040
	ds_read_b128 v[72:75], v128 offset:18432
	ds_read_b128 v[68:71], v131 offset:59904
	ds_read_b128 v[100:103], v131 offset:55296
	ds_read_b128 v[88:91], v128 offset:18464
	ds_read_b128 v[92:95], v128 offset:23072
	ds_read_b128 v[104:107], v131 offset:55328
	ds_read_b128 v[108:111], v131 offset:59936
	s_waitcnt lgkmcnt(4)
	v_mfma_f32_32x32x16_bf16 v[32:47], v[100:103], v[72:75], v[32:47]
	v_mfma_f32_32x32x16_bf16 v[48:63], v[68:71], v[72:75], v[48:63]
	v_mfma_f32_32x32x16_bf16 v[16:31], v[100:103], v[64:67], v[16:31]
	v_mfma_f32_32x32x16_bf16 v[0:15], v[68:71], v[64:67], v[0:15]
	global_load_dwordx4 v[64:67], v168, s[8:9] offset:640
	global_load_dwordx4 v[68:71], v169, s[8:9] offset:640
	global_load_dwordx4 v[72:75], v170, s[8:9] offset:640
	global_load_dwordx4 v[100:103], v171, s[8:9] offset:640
	global_load_dwordx4 v[172:175], v168, s[10:11] offset:640
	global_load_dwordx4 v[176:179], v169, s[10:11] offset:640
	global_load_dwordx4 v[180:183], v170, s[10:11] offset:640
	global_load_dwordx4 v[196:199], v171, s[10:11] offset:640
	ds_read_b128 v[200:203], v128 offset:18496
	ds_read_b128 v[210:213], v128 offset:23104
	ds_read_b128 v[214:217], v131 offset:55360
	ds_read_b128 v[218:221], v131 offset:59968
	s_waitcnt vmcnt(15)
	ds_write_b128 v130, v[76:79]
	s_waitcnt vmcnt(14)
	ds_write_b128 v130, v[80:83] offset:4608
	s_waitcnt vmcnt(13)
	ds_write_b128 v130, v[84:87] offset:9216
	s_waitcnt vmcnt(12)
	ds_write_b128 v130, v[96:99] offset:13824
	s_waitcnt lgkmcnt(9)
	v_mfma_f32_32x32x16_bf16 v[32:47], v[104:107], v[88:91], v[32:47]
	s_waitcnt lgkmcnt(8)
	v_mfma_f32_32x32x16_bf16 v[48:63], v[108:111], v[88:91], v[48:63]
	v_mfma_f32_32x32x16_bf16 v[16:31], v[104:107], v[92:95], v[16:31]
	v_mfma_f32_32x32x16_bf16 v[0:15], v[108:111], v[92:95], v[0:15]
	ds_read_b128 v[76:79], v128 offset:18528
	ds_read_b128 v[80:83], v128 offset:23136
	ds_read_b128 v[84:87], v131 offset:55392
	ds_read_b128 v[88:91], v131 offset:60000
	s_waitcnt vmcnt(11)
	ds_write_b128 v130, v[112:115] offset:36864
	s_waitcnt vmcnt(10)
	ds_write_b128 v130, v[116:119] offset:41472
	s_waitcnt vmcnt(9)
	ds_write_b128 v130, v[120:123] offset:46080
	s_waitcnt vmcnt(8)
	ds_write_b128 v130, v[124:127] offset:50688
	s_waitcnt lgkmcnt(13)
	v_mfma_f32_32x32x16_bf16 v[32:47], v[214:217], v[200:203], v[32:47]
	s_waitcnt lgkmcnt(0)
	s_barrier
	v_mfma_f32_32x32x16_bf16 v[48:63], v[218:221], v[200:203], v[48:63]
	v_mfma_f32_32x32x16_bf16 v[16:31], v[214:217], v[210:213], v[16:31]
	v_mfma_f32_32x32x16_bf16 v[0:15], v[218:221], v[210:213], v[0:15]
	v_mfma_f32_32x32x16_bf16 v[32:47], v[84:87], v[76:79], v[32:47]
	v_mfma_f32_32x32x16_bf16 v[48:63], v[88:91], v[76:79], v[48:63]
	v_mfma_f32_32x32x16_bf16 v[16:31], v[84:87], v[80:83], v[16:31]
	v_mfma_f32_32x32x16_bf16 v[0:15], v[88:91], v[80:83], v[0:15]
	ds_read_b128 v[76:79], v128 offset:4608
	ds_read_b128 v[84:87], v128
	ds_read_b128 v[80:83], v131 offset:41472
	ds_read_b128 v[96:99], v131 offset:36864
	ds_read_b128 v[88:91], v128 offset:32
	ds_read_b128 v[92:95], v128 offset:4640
	ds_read_b128 v[104:107], v131 offset:36896
	ds_read_b128 v[108:111], v131 offset:41504
	s_waitcnt lgkmcnt(4)
	v_mfma_f32_32x32x16_bf16 v[32:47], v[96:99], v[84:87], v[32:47]
	v_mfma_f32_32x32x16_bf16 v[48:63], v[80:83], v[84:87], v[48:63]
	v_mfma_f32_32x32x16_bf16 v[16:31], v[96:99], v[76:79], v[16:31]
	v_mfma_f32_32x32x16_bf16 v[0:15], v[80:83], v[76:79], v[0:15]
	global_load_dwordx4 v[76:79], v168, s[8:9] offset:768
	global_load_dwordx4 v[80:83], v169, s[8:9] offset:768
	global_load_dwordx4 v[84:87], v170, s[8:9] offset:768
	global_load_dwordx4 v[96:99], v171, s[8:9] offset:768
	global_load_dwordx4 v[112:115], v168, s[10:11] offset:768
	global_load_dwordx4 v[116:119], v169, s[10:11] offset:768
	global_load_dwordx4 v[120:123], v170, s[10:11] offset:768
	global_load_dwordx4 v[124:127], v171, s[10:11] offset:768
	ds_read_b128 v[200:203], v128 offset:64
	ds_read_b128 v[210:213], v128 offset:4672
	ds_read_b128 v[214:217], v131 offset:36928
	ds_read_b128 v[218:221], v131 offset:41536
	s_waitcnt vmcnt(15)
	ds_write_b128 v130, v[64:67] offset:18432
	s_waitcnt vmcnt(14)
	ds_write_b128 v130, v[68:71] offset:23040
	s_waitcnt vmcnt(13)
	ds_write_b128 v130, v[72:75] offset:27648
	s_waitcnt vmcnt(12)
	ds_write_b128 v130, v[100:103] offset:32256
	s_waitcnt lgkmcnt(9)
	v_mfma_f32_32x32x16_bf16 v[32:47], v[104:107], v[88:91], v[32:47]
	s_waitcnt lgkmcnt(8)
	v_mfma_f32_32x32x16_bf16 v[48:63], v[108:111], v[88:91], v[48:63]
	v_mfma_f32_32x32x16_bf16 v[16:31], v[104:107], v[92:95], v[16:31]
	v_mfma_f32_32x32x16_bf16 v[0:15], v[108:111], v[92:95], v[0:15]
	ds_read_b128 v[64:67], v128 offset:96
	ds_read_b128 v[68:71], v128 offset:4704
	ds_read_b128 v[72:75], v131 offset:36960
	ds_read_b128 v[88:91], v131 offset:41568
	s_waitcnt vmcnt(11)
	ds_write_b128 v130, v[172:175] offset:55296
	s_waitcnt vmcnt(10)
	ds_write_b128 v130, v[176:179] offset:59904
	s_waitcnt vmcnt(9)
	ds_write_b128 v130, v[180:183] offset:64512
	s_waitcnt vmcnt(8)
	ds_write_b128 v129, v[196:199] offset:13824
	s_waitcnt lgkmcnt(13)
	v_mfma_f32_32x32x16_bf16 v[32:47], v[214:217], v[200:203], v[32:47]
	s_waitcnt lgkmcnt(0)
	s_barrier
	v_mfma_f32_32x32x16_bf16 v[48:63], v[218:221], v[200:203], v[48:63]
	v_mfma_f32_32x32x16_bf16 v[16:31], v[214:217], v[210:213], v[16:31]
	v_mfma_f32_32x32x16_bf16 v[0:15], v[218:221], v[210:213], v[0:15]
	v_mfma_f32_32x32x16_bf16 v[32:47], v[72:75], v[64:67], v[32:47]
	v_mfma_f32_32x32x16_bf16 v[48:63], v[88:91], v[64:67], v[48:63]
	v_mfma_f32_32x32x16_bf16 v[16:31], v[72:75], v[68:71], v[16:31]
	v_mfma_f32_32x32x16_bf16 v[0:15], v[88:91], v[68:71], v[0:15]
	ds_read_b128 v[64:67], v128 offset:23040
	ds_read_b128 v[72:75], v128 offset:18432
	ds_read_b128 v[68:71], v131 offset:59904
	ds_read_b128 v[100:103], v131 offset:55296
	ds_read_b128 v[88:91], v128 offset:18464
	ds_read_b128 v[92:95], v128 offset:23072
	ds_read_b128 v[104:107], v131 offset:55328
	ds_read_b128 v[108:111], v131 offset:59936
	s_waitcnt lgkmcnt(4)
	v_mfma_f32_32x32x16_bf16 v[32:47], v[100:103], v[72:75], v[32:47]
	v_mfma_f32_32x32x16_bf16 v[48:63], v[68:71], v[72:75], v[48:63]
	v_mfma_f32_32x32x16_bf16 v[16:31], v[100:103], v[64:67], v[16:31]
	v_mfma_f32_32x32x16_bf16 v[0:15], v[68:71], v[64:67], v[0:15]
	global_load_dwordx4 v[64:67], v168, s[8:9] offset:896
	global_load_dwordx4 v[68:71], v169, s[8:9] offset:896
	global_load_dwordx4 v[72:75], v170, s[8:9] offset:896
	global_load_dwordx4 v[100:103], v171, s[8:9] offset:896
	global_load_dwordx4 v[172:175], v168, s[10:11] offset:896
	global_load_dwordx4 v[176:179], v169, s[10:11] offset:896
	global_load_dwordx4 v[180:183], v170, s[10:11] offset:896
	global_load_dwordx4 v[196:199], v171, s[10:11] offset:896
	ds_read_b128 v[200:203], v128 offset:18496
	ds_read_b128 v[210:213], v128 offset:23104
	ds_read_b128 v[214:217], v131 offset:55360
	ds_read_b128 v[218:221], v131 offset:59968
	s_waitcnt vmcnt(15)
	ds_write_b128 v130, v[76:79]
	s_waitcnt vmcnt(14)
	ds_write_b128 v130, v[80:83] offset:4608
	s_waitcnt vmcnt(13)
	ds_write_b128 v130, v[84:87] offset:9216
	s_waitcnt vmcnt(12)
	ds_write_b128 v130, v[96:99] offset:13824
	s_waitcnt lgkmcnt(9)
	v_mfma_f32_32x32x16_bf16 v[32:47], v[104:107], v[88:91], v[32:47]
	s_waitcnt lgkmcnt(8)
	v_mfma_f32_32x32x16_bf16 v[48:63], v[108:111], v[88:91], v[48:63]
	v_mfma_f32_32x32x16_bf16 v[16:31], v[104:107], v[92:95], v[16:31]
	v_mfma_f32_32x32x16_bf16 v[0:15], v[108:111], v[92:95], v[0:15]
	ds_read_b128 v[76:79], v128 offset:18528
	ds_read_b128 v[80:83], v128 offset:23136
	ds_read_b128 v[84:87], v131 offset:55392
	ds_read_b128 v[88:91], v131 offset:60000
	s_waitcnt vmcnt(11)
	ds_write_b128 v130, v[112:115] offset:36864
	s_waitcnt vmcnt(10)
	ds_write_b128 v130, v[116:119] offset:41472
	s_waitcnt vmcnt(9)
	ds_write_b128 v130, v[120:123] offset:46080
	s_waitcnt vmcnt(8)
	ds_write_b128 v130, v[124:127] offset:50688
	s_waitcnt lgkmcnt(13)
	v_mfma_f32_32x32x16_bf16 v[32:47], v[214:217], v[200:203], v[32:47]
	s_waitcnt lgkmcnt(0)
	s_barrier
	v_mfma_f32_32x32x16_bf16 v[48:63], v[218:221], v[200:203], v[48:63]
	v_mfma_f32_32x32x16_bf16 v[16:31], v[214:217], v[210:213], v[16:31]
	v_mfma_f32_32x32x16_bf16 v[0:15], v[218:221], v[210:213], v[0:15]
	v_mfma_f32_32x32x16_bf16 v[32:47], v[84:87], v[76:79], v[32:47]
	v_mfma_f32_32x32x16_bf16 v[48:63], v[88:91], v[76:79], v[48:63]
	v_mfma_f32_32x32x16_bf16 v[16:31], v[84:87], v[80:83], v[16:31]
	v_mfma_f32_32x32x16_bf16 v[0:15], v[88:91], v[80:83], v[0:15]
	ds_read_b128 v[76:79], v128 offset:4608
	ds_read_b128 v[84:87], v128
	ds_read_b128 v[80:83], v131 offset:41472
	ds_read_b128 v[96:99], v131 offset:36864
	ds_read_b128 v[88:91], v128 offset:32
	ds_read_b128 v[92:95], v128 offset:4640
	ds_read_b128 v[104:107], v131 offset:36896
	ds_read_b128 v[108:111], v131 offset:41504
	s_waitcnt lgkmcnt(4)
	v_mfma_f32_32x32x16_bf16 v[32:47], v[96:99], v[84:87], v[32:47]
	v_mfma_f32_32x32x16_bf16 v[48:63], v[80:83], v[84:87], v[48:63]
	v_mfma_f32_32x32x16_bf16 v[16:31], v[96:99], v[76:79], v[16:31]
	v_mfma_f32_32x32x16_bf16 v[0:15], v[80:83], v[76:79], v[0:15]
	global_load_dwordx4 v[76:79], v168, s[8:9] offset:1024
	global_load_dwordx4 v[80:83], v169, s[8:9] offset:1024
	global_load_dwordx4 v[84:87], v170, s[8:9] offset:1024
	global_load_dwordx4 v[96:99], v171, s[8:9] offset:1024
	global_load_dwordx4 v[112:115], v168, s[10:11] offset:1024
	global_load_dwordx4 v[116:119], v169, s[10:11] offset:1024
	global_load_dwordx4 v[120:123], v170, s[10:11] offset:1024
	global_load_dwordx4 v[124:127], v171, s[10:11] offset:1024
	ds_read_b128 v[200:203], v128 offset:64
	ds_read_b128 v[210:213], v128 offset:4672
	ds_read_b128 v[214:217], v131 offset:36928
	ds_read_b128 v[218:221], v131 offset:41536
	s_waitcnt vmcnt(15)
	ds_write_b128 v130, v[64:67] offset:18432
	s_waitcnt vmcnt(14)
	ds_write_b128 v130, v[68:71] offset:23040
	s_waitcnt vmcnt(13)
	ds_write_b128 v130, v[72:75] offset:27648
	s_waitcnt vmcnt(12)
	ds_write_b128 v130, v[100:103] offset:32256
	s_waitcnt lgkmcnt(9)
	v_mfma_f32_32x32x16_bf16 v[32:47], v[104:107], v[88:91], v[32:47]
	s_waitcnt lgkmcnt(8)
	v_mfma_f32_32x32x16_bf16 v[48:63], v[108:111], v[88:91], v[48:63]
	v_mfma_f32_32x32x16_bf16 v[16:31], v[104:107], v[92:95], v[16:31]
	v_mfma_f32_32x32x16_bf16 v[0:15], v[108:111], v[92:95], v[0:15]
	ds_read_b128 v[64:67], v128 offset:96
	ds_read_b128 v[68:71], v128 offset:4704
	ds_read_b128 v[72:75], v131 offset:36960
	ds_read_b128 v[88:91], v131 offset:41568
	s_waitcnt vmcnt(11)
	ds_write_b128 v130, v[172:175] offset:55296
	s_waitcnt vmcnt(10)
	ds_write_b128 v130, v[176:179] offset:59904
	s_waitcnt vmcnt(9)
	ds_write_b128 v130, v[180:183] offset:64512
	s_waitcnt vmcnt(8)
	ds_write_b128 v129, v[196:199] offset:13824
	s_waitcnt lgkmcnt(13)
	v_mfma_f32_32x32x16_bf16 v[32:47], v[214:217], v[200:203], v[32:47]
	s_waitcnt lgkmcnt(0)
	s_barrier
	v_mfma_f32_32x32x16_bf16 v[48:63], v[218:221], v[200:203], v[48:63]
	v_mfma_f32_32x32x16_bf16 v[16:31], v[214:217], v[210:213], v[16:31]
	v_mfma_f32_32x32x16_bf16 v[0:15], v[218:221], v[210:213], v[0:15]
	v_mfma_f32_32x32x16_bf16 v[32:47], v[72:75], v[64:67], v[32:47]
	v_mfma_f32_32x32x16_bf16 v[48:63], v[88:91], v[64:67], v[48:63]
	v_mfma_f32_32x32x16_bf16 v[16:31], v[72:75], v[68:71], v[16:31]
	v_mfma_f32_32x32x16_bf16 v[0:15], v[88:91], v[68:71], v[0:15]
	ds_read_b128 v[64:67], v128 offset:23040
	ds_read_b128 v[72:75], v128 offset:18432
	ds_read_b128 v[68:71], v131 offset:59904
	ds_read_b128 v[100:103], v131 offset:55296
	ds_read_b128 v[88:91], v128 offset:18464
	ds_read_b128 v[92:95], v128 offset:23072
	ds_read_b128 v[104:107], v131 offset:55328
	ds_read_b128 v[108:111], v131 offset:59936
	s_waitcnt lgkmcnt(4)
	v_mfma_f32_32x32x16_bf16 v[32:47], v[100:103], v[72:75], v[32:47]
	v_mfma_f32_32x32x16_bf16 v[48:63], v[68:71], v[72:75], v[48:63]
	v_mfma_f32_32x32x16_bf16 v[16:31], v[100:103], v[64:67], v[16:31]
	v_mfma_f32_32x32x16_bf16 v[0:15], v[68:71], v[64:67], v[0:15]
	global_load_dwordx4 v[64:67], v168, s[8:9] offset:1152
	global_load_dwordx4 v[68:71], v169, s[8:9] offset:1152
	global_load_dwordx4 v[72:75], v170, s[8:9] offset:1152
	global_load_dwordx4 v[100:103], v171, s[8:9] offset:1152
	global_load_dwordx4 v[172:175], v168, s[10:11] offset:1152
	global_load_dwordx4 v[176:179], v169, s[10:11] offset:1152
	global_load_dwordx4 v[180:183], v170, s[10:11] offset:1152
	global_load_dwordx4 v[196:199], v171, s[10:11] offset:1152
	ds_read_b128 v[200:203], v128 offset:18496
	ds_read_b128 v[210:213], v128 offset:23104
	ds_read_b128 v[214:217], v131 offset:55360
	ds_read_b128 v[218:221], v131 offset:59968
	s_waitcnt vmcnt(15)
	ds_write_b128 v130, v[76:79]
	s_waitcnt vmcnt(14)
	ds_write_b128 v130, v[80:83] offset:4608
	s_waitcnt vmcnt(13)
	ds_write_b128 v130, v[84:87] offset:9216
	s_waitcnt vmcnt(12)
	ds_write_b128 v130, v[96:99] offset:13824
	s_waitcnt lgkmcnt(9)
	v_mfma_f32_32x32x16_bf16 v[32:47], v[104:107], v[88:91], v[32:47]
	s_waitcnt lgkmcnt(8)
	v_mfma_f32_32x32x16_bf16 v[48:63], v[108:111], v[88:91], v[48:63]
	v_mfma_f32_32x32x16_bf16 v[16:31], v[104:107], v[92:95], v[16:31]
	v_mfma_f32_32x32x16_bf16 v[0:15], v[108:111], v[92:95], v[0:15]
	ds_read_b128 v[76:79], v128 offset:18528
	ds_read_b128 v[80:83], v128 offset:23136
	ds_read_b128 v[84:87], v131 offset:55392
	ds_read_b128 v[88:91], v131 offset:60000
	s_waitcnt vmcnt(11)
	ds_write_b128 v130, v[112:115] offset:36864
	s_waitcnt vmcnt(10)
	ds_write_b128 v130, v[116:119] offset:41472
	s_waitcnt vmcnt(9)
	ds_write_b128 v130, v[120:123] offset:46080
	s_waitcnt vmcnt(8)
	ds_write_b128 v130, v[124:127] offset:50688
	s_waitcnt lgkmcnt(13)
	v_mfma_f32_32x32x16_bf16 v[32:47], v[214:217], v[200:203], v[32:47]
	s_waitcnt lgkmcnt(0)
	s_barrier
	v_mfma_f32_32x32x16_bf16 v[48:63], v[218:221], v[200:203], v[48:63]
	v_mfma_f32_32x32x16_bf16 v[16:31], v[214:217], v[210:213], v[16:31]
	v_mfma_f32_32x32x16_bf16 v[0:15], v[218:221], v[210:213], v[0:15]
	v_mfma_f32_32x32x16_bf16 v[32:47], v[84:87], v[76:79], v[32:47]
	v_mfma_f32_32x32x16_bf16 v[48:63], v[88:91], v[76:79], v[48:63]
	v_mfma_f32_32x32x16_bf16 v[16:31], v[84:87], v[80:83], v[16:31]
	v_mfma_f32_32x32x16_bf16 v[0:15], v[88:91], v[80:83], v[0:15]
	ds_read_b128 v[76:79], v128 offset:4608
	ds_read_b128 v[84:87], v128
	ds_read_b128 v[80:83], v131 offset:41472
	ds_read_b128 v[96:99], v131 offset:36864
	ds_read_b128 v[88:91], v128 offset:32
	ds_read_b128 v[92:95], v128 offset:4640
	ds_read_b128 v[104:107], v131 offset:36896
	ds_read_b128 v[108:111], v131 offset:41504
	s_waitcnt lgkmcnt(4)
	v_mfma_f32_32x32x16_bf16 v[32:47], v[96:99], v[84:87], v[32:47]
	v_mfma_f32_32x32x16_bf16 v[48:63], v[80:83], v[84:87], v[48:63]
	v_mfma_f32_32x32x16_bf16 v[16:31], v[96:99], v[76:79], v[16:31]
	v_mfma_f32_32x32x16_bf16 v[0:15], v[80:83], v[76:79], v[0:15]
	global_load_dwordx4 v[76:79], v168, s[8:9] offset:1280
	global_load_dwordx4 v[80:83], v169, s[8:9] offset:1280
	global_load_dwordx4 v[84:87], v170, s[8:9] offset:1280
	global_load_dwordx4 v[96:99], v171, s[8:9] offset:1280
	global_load_dwordx4 v[112:115], v168, s[10:11] offset:1280
	global_load_dwordx4 v[116:119], v169, s[10:11] offset:1280
	global_load_dwordx4 v[120:123], v170, s[10:11] offset:1280
	global_load_dwordx4 v[124:127], v171, s[10:11] offset:1280
	ds_read_b128 v[200:203], v128 offset:64
	ds_read_b128 v[210:213], v128 offset:4672
	ds_read_b128 v[214:217], v131 offset:36928
	ds_read_b128 v[218:221], v131 offset:41536
	s_waitcnt vmcnt(15)
	ds_write_b128 v130, v[64:67] offset:18432
	s_waitcnt vmcnt(14)
	ds_write_b128 v130, v[68:71] offset:23040
	s_waitcnt vmcnt(13)
	ds_write_b128 v130, v[72:75] offset:27648
	s_waitcnt vmcnt(12)
	ds_write_b128 v130, v[100:103] offset:32256
	s_waitcnt lgkmcnt(9)
	v_mfma_f32_32x32x16_bf16 v[32:47], v[104:107], v[88:91], v[32:47]
	s_waitcnt lgkmcnt(8)
	v_mfma_f32_32x32x16_bf16 v[48:63], v[108:111], v[88:91], v[48:63]
	v_mfma_f32_32x32x16_bf16 v[16:31], v[104:107], v[92:95], v[16:31]
	v_mfma_f32_32x32x16_bf16 v[0:15], v[108:111], v[92:95], v[0:15]
	ds_read_b128 v[64:67], v128 offset:96
	ds_read_b128 v[68:71], v128 offset:4704
	ds_read_b128 v[72:75], v131 offset:36960
	ds_read_b128 v[88:91], v131 offset:41568
	s_waitcnt vmcnt(11)
	ds_write_b128 v130, v[172:175] offset:55296
	s_waitcnt vmcnt(10)
	ds_write_b128 v130, v[176:179] offset:59904
	s_waitcnt vmcnt(9)
	ds_write_b128 v130, v[180:183] offset:64512
	s_waitcnt vmcnt(8)
	ds_write_b128 v129, v[196:199] offset:13824
	s_waitcnt lgkmcnt(13)
	v_mfma_f32_32x32x16_bf16 v[32:47], v[214:217], v[200:203], v[32:47]
	s_waitcnt lgkmcnt(0)
	s_barrier
	v_mfma_f32_32x32x16_bf16 v[48:63], v[218:221], v[200:203], v[48:63]
	v_mfma_f32_32x32x16_bf16 v[16:31], v[214:217], v[210:213], v[16:31]
	v_mfma_f32_32x32x16_bf16 v[0:15], v[218:221], v[210:213], v[0:15]
	v_mfma_f32_32x32x16_bf16 v[32:47], v[72:75], v[64:67], v[32:47]
	v_mfma_f32_32x32x16_bf16 v[48:63], v[88:91], v[64:67], v[48:63]
	v_mfma_f32_32x32x16_bf16 v[16:31], v[72:75], v[68:71], v[16:31]
	v_mfma_f32_32x32x16_bf16 v[0:15], v[88:91], v[68:71], v[0:15]
	ds_read_b128 v[64:67], v128 offset:23040
	ds_read_b128 v[72:75], v128 offset:18432
	ds_read_b128 v[68:71], v131 offset:59904
	ds_read_b128 v[100:103], v131 offset:55296
	ds_read_b128 v[88:91], v128 offset:18464
	ds_read_b128 v[92:95], v128 offset:23072
	ds_read_b128 v[104:107], v131 offset:55328
	ds_read_b128 v[108:111], v131 offset:59936
	s_waitcnt lgkmcnt(4)
	v_mfma_f32_32x32x16_bf16 v[32:47], v[100:103], v[72:75], v[32:47]
	v_mfma_f32_32x32x16_bf16 v[48:63], v[68:71], v[72:75], v[48:63]
	v_mfma_f32_32x32x16_bf16 v[16:31], v[100:103], v[64:67], v[16:31]
	v_mfma_f32_32x32x16_bf16 v[0:15], v[68:71], v[64:67], v[0:15]
	global_load_dwordx4 v[64:67], v168, s[8:9] offset:1408
	global_load_dwordx4 v[68:71], v169, s[8:9] offset:1408
	global_load_dwordx4 v[72:75], v170, s[8:9] offset:1408
	global_load_dwordx4 v[100:103], v171, s[8:9] offset:1408
	global_load_dwordx4 v[172:175], v168, s[10:11] offset:1408
	global_load_dwordx4 v[176:179], v169, s[10:11] offset:1408
	global_load_dwordx4 v[180:183], v170, s[10:11] offset:1408
	global_load_dwordx4 v[196:199], v171, s[10:11] offset:1408
	ds_read_b128 v[200:203], v128 offset:18496
	ds_read_b128 v[210:213], v128 offset:23104
	ds_read_b128 v[214:217], v131 offset:55360
	ds_read_b128 v[218:221], v131 offset:59968
	s_waitcnt vmcnt(15)
	ds_write_b128 v130, v[76:79]
	s_waitcnt vmcnt(14)
	ds_write_b128 v130, v[80:83] offset:4608
	s_waitcnt vmcnt(13)
	ds_write_b128 v130, v[84:87] offset:9216
	s_waitcnt vmcnt(12)
	ds_write_b128 v130, v[96:99] offset:13824
	s_waitcnt lgkmcnt(9)
	v_mfma_f32_32x32x16_bf16 v[32:47], v[104:107], v[88:91], v[32:47]
	s_waitcnt lgkmcnt(8)
	v_mfma_f32_32x32x16_bf16 v[48:63], v[108:111], v[88:91], v[48:63]
	v_mfma_f32_32x32x16_bf16 v[16:31], v[104:107], v[92:95], v[16:31]
	v_mfma_f32_32x32x16_bf16 v[0:15], v[108:111], v[92:95], v[0:15]
	ds_read_b128 v[76:79], v128 offset:18528
	ds_read_b128 v[80:83], v128 offset:23136
	ds_read_b128 v[84:87], v131 offset:55392
	ds_read_b128 v[88:91], v131 offset:60000
	s_waitcnt vmcnt(11)
	ds_write_b128 v130, v[112:115] offset:36864
	s_waitcnt vmcnt(10)
	ds_write_b128 v130, v[116:119] offset:41472
	s_waitcnt vmcnt(9)
	ds_write_b128 v130, v[120:123] offset:46080
	s_waitcnt vmcnt(8)
	ds_write_b128 v130, v[124:127] offset:50688
	s_waitcnt lgkmcnt(13)
	v_mfma_f32_32x32x16_bf16 v[32:47], v[214:217], v[200:203], v[32:47]
	s_waitcnt lgkmcnt(0)
	s_barrier
	v_mfma_f32_32x32x16_bf16 v[48:63], v[218:221], v[200:203], v[48:63]
	v_mfma_f32_32x32x16_bf16 v[16:31], v[214:217], v[210:213], v[16:31]
	v_mfma_f32_32x32x16_bf16 v[0:15], v[218:221], v[210:213], v[0:15]
	v_mfma_f32_32x32x16_bf16 v[32:47], v[84:87], v[76:79], v[32:47]
	v_mfma_f32_32x32x16_bf16 v[48:63], v[88:91], v[76:79], v[48:63]
	v_mfma_f32_32x32x16_bf16 v[16:31], v[84:87], v[80:83], v[16:31]
	v_mfma_f32_32x32x16_bf16 v[0:15], v[88:91], v[80:83], v[0:15]
	ds_read_b128 v[76:79], v128 offset:4608
	ds_read_b128 v[84:87], v128
	ds_read_b128 v[80:83], v131 offset:41472
	ds_read_b128 v[96:99], v131 offset:36864
	ds_read_b128 v[88:91], v128 offset:32
	ds_read_b128 v[92:95], v128 offset:4640
	ds_read_b128 v[104:107], v131 offset:36896
	ds_read_b128 v[108:111], v131 offset:41504
	s_waitcnt lgkmcnt(4)
	v_mfma_f32_32x32x16_bf16 v[32:47], v[96:99], v[84:87], v[32:47]
	v_mfma_f32_32x32x16_bf16 v[48:63], v[80:83], v[84:87], v[48:63]
	v_mfma_f32_32x32x16_bf16 v[16:31], v[96:99], v[76:79], v[16:31]
	v_mfma_f32_32x32x16_bf16 v[0:15], v[80:83], v[76:79], v[0:15]
	global_load_dwordx4 v[76:79], v168, s[8:9] offset:1536
	global_load_dwordx4 v[80:83], v169, s[8:9] offset:1536
	global_load_dwordx4 v[84:87], v170, s[8:9] offset:1536
	global_load_dwordx4 v[96:99], v171, s[8:9] offset:1536
	global_load_dwordx4 v[112:115], v168, s[10:11] offset:1536
	global_load_dwordx4 v[116:119], v169, s[10:11] offset:1536
	global_load_dwordx4 v[120:123], v170, s[10:11] offset:1536
	global_load_dwordx4 v[124:127], v171, s[10:11] offset:1536
	ds_read_b128 v[200:203], v128 offset:64
	ds_read_b128 v[210:213], v128 offset:4672
	ds_read_b128 v[214:217], v131 offset:36928
	ds_read_b128 v[218:221], v131 offset:41536
	s_waitcnt vmcnt(15)
	ds_write_b128 v130, v[64:67] offset:18432
	s_waitcnt vmcnt(14)
	ds_write_b128 v130, v[68:71] offset:23040
	s_waitcnt vmcnt(13)
	ds_write_b128 v130, v[72:75] offset:27648
	s_waitcnt vmcnt(12)
	ds_write_b128 v130, v[100:103] offset:32256
	s_waitcnt lgkmcnt(9)
	v_mfma_f32_32x32x16_bf16 v[32:47], v[104:107], v[88:91], v[32:47]
	s_waitcnt lgkmcnt(8)
	v_mfma_f32_32x32x16_bf16 v[48:63], v[108:111], v[88:91], v[48:63]
	v_mfma_f32_32x32x16_bf16 v[16:31], v[104:107], v[92:95], v[16:31]
	v_mfma_f32_32x32x16_bf16 v[0:15], v[108:111], v[92:95], v[0:15]
	ds_read_b128 v[64:67], v128 offset:96
	ds_read_b128 v[68:71], v128 offset:4704
	ds_read_b128 v[72:75], v131 offset:36960
	ds_read_b128 v[88:91], v131 offset:41568
	s_waitcnt vmcnt(11)
	ds_write_b128 v130, v[172:175] offset:55296
	s_waitcnt vmcnt(10)
	ds_write_b128 v130, v[176:179] offset:59904
	s_waitcnt vmcnt(9)
	ds_write_b128 v130, v[180:183] offset:64512
	s_waitcnt vmcnt(8)
	ds_write_b128 v129, v[196:199] offset:13824
	s_waitcnt lgkmcnt(13)
	v_mfma_f32_32x32x16_bf16 v[32:47], v[214:217], v[200:203], v[32:47]
	s_waitcnt lgkmcnt(0)
	s_barrier
	v_mfma_f32_32x32x16_bf16 v[48:63], v[218:221], v[200:203], v[48:63]
	v_mfma_f32_32x32x16_bf16 v[16:31], v[214:217], v[210:213], v[16:31]
	v_mfma_f32_32x32x16_bf16 v[0:15], v[218:221], v[210:213], v[0:15]
	v_mfma_f32_32x32x16_bf16 v[32:47], v[72:75], v[64:67], v[32:47]
	v_mfma_f32_32x32x16_bf16 v[48:63], v[88:91], v[64:67], v[48:63]
	v_mfma_f32_32x32x16_bf16 v[16:31], v[72:75], v[68:71], v[16:31]
	v_mfma_f32_32x32x16_bf16 v[0:15], v[88:91], v[68:71], v[0:15]
	ds_read_b128 v[64:67], v128 offset:23040
	ds_read_b128 v[72:75], v128 offset:18432
	ds_read_b128 v[68:71], v131 offset:59904
	ds_read_b128 v[100:103], v131 offset:55296
	ds_read_b128 v[88:91], v128 offset:18464
	ds_read_b128 v[92:95], v128 offset:23072
	ds_read_b128 v[104:107], v131 offset:55328
	ds_read_b128 v[108:111], v131 offset:59936
	s_waitcnt lgkmcnt(4)
	v_mfma_f32_32x32x16_bf16 v[32:47], v[100:103], v[72:75], v[32:47]
	v_mfma_f32_32x32x16_bf16 v[48:63], v[68:71], v[72:75], v[48:63]
	v_mfma_f32_32x32x16_bf16 v[16:31], v[100:103], v[64:67], v[16:31]
	v_mfma_f32_32x32x16_bf16 v[0:15], v[68:71], v[64:67], v[0:15]
	global_load_dwordx4 v[64:67], v168, s[8:9] offset:1664
	global_load_dwordx4 v[68:71], v169, s[8:9] offset:1664
	global_load_dwordx4 v[72:75], v170, s[8:9] offset:1664
	global_load_dwordx4 v[100:103], v171, s[8:9] offset:1664
	global_load_dwordx4 v[172:175], v168, s[10:11] offset:1664
	global_load_dwordx4 v[176:179], v169, s[10:11] offset:1664
	global_load_dwordx4 v[180:183], v170, s[10:11] offset:1664
	global_load_dwordx4 v[196:199], v171, s[10:11] offset:1664
	ds_read_b128 v[200:203], v128 offset:18496
	ds_read_b128 v[210:213], v128 offset:23104
	ds_read_b128 v[214:217], v131 offset:55360
	ds_read_b128 v[218:221], v131 offset:59968
	s_waitcnt vmcnt(15)
	ds_write_b128 v130, v[76:79]
	s_waitcnt vmcnt(14)
	ds_write_b128 v130, v[80:83] offset:4608
	s_waitcnt vmcnt(13)
	ds_write_b128 v130, v[84:87] offset:9216
	s_waitcnt vmcnt(12)
	ds_write_b128 v130, v[96:99] offset:13824
	s_waitcnt lgkmcnt(9)
	v_mfma_f32_32x32x16_bf16 v[32:47], v[104:107], v[88:91], v[32:47]
	s_waitcnt lgkmcnt(8)
	v_mfma_f32_32x32x16_bf16 v[48:63], v[108:111], v[88:91], v[48:63]
	v_mfma_f32_32x32x16_bf16 v[16:31], v[104:107], v[92:95], v[16:31]
	v_mfma_f32_32x32x16_bf16 v[0:15], v[108:111], v[92:95], v[0:15]
	ds_read_b128 v[76:79], v128 offset:18528
	ds_read_b128 v[80:83], v128 offset:23136
	ds_read_b128 v[84:87], v131 offset:55392
	ds_read_b128 v[88:91], v131 offset:60000
	s_waitcnt vmcnt(11)
	ds_write_b128 v130, v[112:115] offset:36864
	s_waitcnt vmcnt(10)
	ds_write_b128 v130, v[116:119] offset:41472
	s_waitcnt vmcnt(9)
	ds_write_b128 v130, v[120:123] offset:46080
	s_waitcnt vmcnt(8)
	ds_write_b128 v130, v[124:127] offset:50688
	s_waitcnt lgkmcnt(13)
	v_mfma_f32_32x32x16_bf16 v[32:47], v[214:217], v[200:203], v[32:47]
	s_waitcnt lgkmcnt(0)
	s_barrier
	v_mfma_f32_32x32x16_bf16 v[48:63], v[218:221], v[200:203], v[48:63]
	v_mfma_f32_32x32x16_bf16 v[16:31], v[214:217], v[210:213], v[16:31]
	v_mfma_f32_32x32x16_bf16 v[0:15], v[218:221], v[210:213], v[0:15]
	v_mfma_f32_32x32x16_bf16 v[32:47], v[84:87], v[76:79], v[32:47]
	v_mfma_f32_32x32x16_bf16 v[48:63], v[88:91], v[76:79], v[48:63]
	v_mfma_f32_32x32x16_bf16 v[16:31], v[84:87], v[80:83], v[16:31]
	v_mfma_f32_32x32x16_bf16 v[0:15], v[88:91], v[80:83], v[0:15]
	ds_read_b128 v[76:79], v128 offset:4608
	ds_read_b128 v[84:87], v128
	ds_read_b128 v[80:83], v131 offset:41472
	ds_read_b128 v[96:99], v131 offset:36864
	ds_read_b128 v[88:91], v128 offset:32
	ds_read_b128 v[92:95], v128 offset:4640
	ds_read_b128 v[104:107], v131 offset:36896
	ds_read_b128 v[108:111], v131 offset:41504
	s_waitcnt lgkmcnt(4)
	v_mfma_f32_32x32x16_bf16 v[32:47], v[96:99], v[84:87], v[32:47]
	v_mfma_f32_32x32x16_bf16 v[48:63], v[80:83], v[84:87], v[48:63]
	v_mfma_f32_32x32x16_bf16 v[16:31], v[96:99], v[76:79], v[16:31]
	v_mfma_f32_32x32x16_bf16 v[0:15], v[80:83], v[76:79], v[0:15]
	global_load_dwordx4 v[76:79], v168, s[8:9] offset:1792
	global_load_dwordx4 v[80:83], v169, s[8:9] offset:1792
	global_load_dwordx4 v[84:87], v170, s[8:9] offset:1792
	global_load_dwordx4 v[96:99], v171, s[8:9] offset:1792
	global_load_dwordx4 v[112:115], v168, s[10:11] offset:1792
	global_load_dwordx4 v[116:119], v169, s[10:11] offset:1792
	global_load_dwordx4 v[120:123], v170, s[10:11] offset:1792
	global_load_dwordx4 v[124:127], v171, s[10:11] offset:1792
	ds_read_b128 v[200:203], v128 offset:64
	ds_read_b128 v[210:213], v128 offset:4672
	ds_read_b128 v[214:217], v131 offset:36928
	ds_read_b128 v[218:221], v131 offset:41536
	s_waitcnt vmcnt(15)
	ds_write_b128 v130, v[64:67] offset:18432
	s_waitcnt vmcnt(14)
	ds_write_b128 v130, v[68:71] offset:23040
	s_waitcnt vmcnt(13)
	ds_write_b128 v130, v[72:75] offset:27648
	s_waitcnt vmcnt(12)
	ds_write_b128 v130, v[100:103] offset:32256
	s_waitcnt lgkmcnt(9)
	v_mfma_f32_32x32x16_bf16 v[32:47], v[104:107], v[88:91], v[32:47]
	s_waitcnt lgkmcnt(8)
	v_mfma_f32_32x32x16_bf16 v[48:63], v[108:111], v[88:91], v[48:63]
	v_mfma_f32_32x32x16_bf16 v[16:31], v[104:107], v[92:95], v[16:31]
	v_mfma_f32_32x32x16_bf16 v[0:15], v[108:111], v[92:95], v[0:15]
	ds_read_b128 v[64:67], v128 offset:96
	ds_read_b128 v[68:71], v128 offset:4704
	ds_read_b128 v[72:75], v131 offset:36960
	ds_read_b128 v[88:91], v131 offset:41568
	s_waitcnt vmcnt(11)
	ds_write_b128 v130, v[172:175] offset:55296
	s_waitcnt vmcnt(10)
	ds_write_b128 v130, v[176:179] offset:59904
	s_waitcnt vmcnt(9)
	ds_write_b128 v130, v[180:183] offset:64512
	s_waitcnt vmcnt(8)
	ds_write_b128 v129, v[196:199] offset:13824
	s_waitcnt lgkmcnt(13)
	v_mfma_f32_32x32x16_bf16 v[32:47], v[214:217], v[200:203], v[32:47]
	s_waitcnt lgkmcnt(0)
	s_barrier
	v_mfma_f32_32x32x16_bf16 v[48:63], v[218:221], v[200:203], v[48:63]
	v_mfma_f32_32x32x16_bf16 v[16:31], v[214:217], v[210:213], v[16:31]
	v_mfma_f32_32x32x16_bf16 v[0:15], v[218:221], v[210:213], v[0:15]
	v_mfma_f32_32x32x16_bf16 v[32:47], v[72:75], v[64:67], v[32:47]
	v_mfma_f32_32x32x16_bf16 v[48:63], v[88:91], v[64:67], v[48:63]
	v_mfma_f32_32x32x16_bf16 v[16:31], v[72:75], v[68:71], v[16:31]
	v_mfma_f32_32x32x16_bf16 v[0:15], v[88:91], v[68:71], v[0:15]
	ds_read_b128 v[64:67], v128 offset:23040
	ds_read_b128 v[72:75], v128 offset:18432
	ds_read_b128 v[68:71], v131 offset:59904
	ds_read_b128 v[100:103], v131 offset:55296
	ds_read_b128 v[88:91], v128 offset:18464
	ds_read_b128 v[92:95], v128 offset:23072
	ds_read_b128 v[104:107], v131 offset:55328
	ds_read_b128 v[108:111], v131 offset:59936
	s_waitcnt lgkmcnt(4)
	v_mfma_f32_32x32x16_bf16 v[32:47], v[100:103], v[72:75], v[32:47]
	v_mfma_f32_32x32x16_bf16 v[48:63], v[68:71], v[72:75], v[48:63]
	v_mfma_f32_32x32x16_bf16 v[16:31], v[100:103], v[64:67], v[16:31]
	v_mfma_f32_32x32x16_bf16 v[0:15], v[68:71], v[64:67], v[0:15]
	global_load_dwordx4 v[64:67], v168, s[8:9] offset:1920
	global_load_dwordx4 v[68:71], v169, s[8:9] offset:1920
	global_load_dwordx4 v[72:75], v170, s[8:9] offset:1920
	global_load_dwordx4 v[100:103], v171, s[8:9] offset:1920
	global_load_dwordx4 v[172:175], v168, s[10:11] offset:1920
	global_load_dwordx4 v[176:179], v169, s[10:11] offset:1920
	global_load_dwordx4 v[180:183], v170, s[10:11] offset:1920
	s_nop 0
	global_load_dwordx4 v[168:171], v171, s[10:11] offset:1920
	ds_read_b128 v[196:199], v128 offset:18496
	ds_read_b128 v[200:203], v128 offset:23104
	ds_read_b128 v[210:213], v131 offset:55360
	ds_read_b128 v[214:217], v131 offset:59968
	s_waitcnt vmcnt(15)
	ds_write_b128 v130, v[76:79]
	s_waitcnt vmcnt(14)
	ds_write_b128 v130, v[80:83] offset:4608
	s_waitcnt vmcnt(13)
	ds_write_b128 v130, v[84:87] offset:9216
	s_waitcnt vmcnt(12)
	ds_write_b128 v130, v[96:99] offset:13824
	s_waitcnt lgkmcnt(9)
	v_mfma_f32_32x32x16_bf16 v[32:47], v[104:107], v[88:91], v[32:47]
	s_waitcnt lgkmcnt(8)
	v_mfma_f32_32x32x16_bf16 v[48:63], v[108:111], v[88:91], v[48:63]
	v_mfma_f32_32x32x16_bf16 v[0:15], v[108:111], v[92:95], v[0:15]
	v_mfma_f32_32x32x16_bf16 v[16:31], v[104:107], v[92:95], v[16:31]
	ds_read_b128 v[76:79], v128 offset:18528
	ds_read_b128 v[80:83], v128 offset:23136
	ds_read_b128 v[84:87], v131 offset:55392
	ds_read_b128 v[88:91], v131 offset:60000
	s_waitcnt vmcnt(11)
	ds_write_b128 v130, v[112:115] offset:36864
	s_waitcnt vmcnt(10)
	ds_write_b128 v130, v[116:119] offset:41472
	s_waitcnt vmcnt(9)
	ds_write_b128 v130, v[120:123] offset:46080
	s_waitcnt vmcnt(8)
	ds_write_b128 v130, v[124:127] offset:50688
	s_waitcnt lgkmcnt(13)
	v_mfma_f32_32x32x16_bf16 v[32:47], v[210:213], v[196:199], v[32:47]
	s_waitcnt lgkmcnt(0)
	s_barrier
	ds_read_b128 v[92:95], v128
	ds_read_b128 v[96:99], v128 offset:32
	ds_read_b128 v[104:107], v131 offset:36928
	ds_read_b128 v[108:111], v131 offset:41536
	v_mfma_f32_32x32x16_bf16 v[48:63], v[214:217], v[196:199], v[48:63]
	v_mfma_f32_32x32x16_bf16 v[0:15], v[214:217], v[200:203], v[0:15]
	v_mfma_f32_32x32x16_bf16 v[16:31], v[210:213], v[200:203], v[16:31]
	v_mfma_f32_32x32x16_bf16 v[32:47], v[84:87], v[76:79], v[32:47]
	v_mfma_f32_32x32x16_bf16 v[48:63], v[88:91], v[76:79], v[48:63]
	ds_read_b128 v[76:79], v128 offset:4608
	v_mfma_f32_32x32x16_bf16 v[0:15], v[88:91], v[80:83], v[0:15]
	ds_read_b128 v[88:91], v131 offset:36896
	v_mfma_f32_32x32x16_bf16 v[16:31], v[84:87], v[80:83], v[16:31]
	ds_read_b128 v[80:83], v131 offset:41472
	ds_read_b128 v[84:87], v131 offset:36864
	s_waitcnt lgkmcnt(1)
	v_mfma_f32_32x32x16_bf16 v[48:63], v[80:83], v[92:95], v[48:63]
	v_mfma_f32_32x32x16_bf16 v[0:15], v[80:83], v[76:79], v[0:15]
	ds_read_b128 v[80:83], v128 offset:4640
	s_waitcnt lgkmcnt(1)
	v_mfma_f32_32x32x16_bf16 v[32:47], v[84:87], v[92:95], v[32:47]
	ds_read_b128 v[92:95], v128 offset:4672
	v_mfma_f32_32x32x16_bf16 v[16:31], v[84:87], v[76:79], v[16:31]
	ds_read_b128 v[76:79], v131 offset:41504
	ds_read_b128 v[84:87], v128 offset:64
	s_waitcnt vmcnt(7)
	ds_write_b128 v130, v[64:67] offset:18432
	s_waitcnt vmcnt(6)
	ds_write_b128 v130, v[68:71] offset:23040
	s_waitcnt vmcnt(5)
	ds_write_b128 v130, v[72:75] offset:27648
	s_waitcnt vmcnt(4)
	ds_write_b128 v130, v[100:103] offset:32256
	ds_read_b128 v[64:67], v128 offset:96
	v_mfma_f32_32x32x16_bf16 v[32:47], v[88:91], v[96:99], v[32:47]
	ds_read_b128 v[68:71], v128 offset:4704
	ds_read_b128 v[72:75], v131 offset:36960
	s_waitcnt lgkmcnt(10)
	v_mfma_f32_32x32x16_bf16 v[16:31], v[88:91], v[80:83], v[16:31]
	s_waitcnt lgkmcnt(8)
	v_mfma_f32_32x32x16_bf16 v[48:63], v[76:79], v[96:99], v[48:63]
	v_mfma_f32_32x32x16_bf16 v[0:15], v[76:79], v[80:83], v[0:15]
	ds_read_b128 v[76:79], v131 offset:41568
	s_waitcnt vmcnt(3)
	ds_write_b128 v130, v[172:175] offset:55296
	s_waitcnt vmcnt(2)
	ds_write_b128 v130, v[176:179] offset:59904
	s_waitcnt vmcnt(1)
	ds_write_b128 v130, v[180:183] offset:64512
	s_waitcnt vmcnt(0)
	ds_write_b128 v129, v[168:171] offset:13824
	s_waitcnt lgkmcnt(0)
	s_barrier
	v_mfma_f32_32x32x16_bf16 v[32:47], v[104:107], v[84:87], v[32:47]
	ds_read_b128 v[96:99], v128 offset:18464
	ds_read_b128 v[100:103], v128 offset:23072
	ds_read_b128 v[80:83], v131 offset:55360
	ds_read_b128 v[88:91], v131 offset:55392
	v_mfma_f32_32x32x16_bf16 v[16:31], v[104:107], v[92:95], v[16:31]
	ds_read_b128 v[104:107], v131 offset:55328
	v_mfma_f32_32x32x16_bf16 v[48:63], v[108:111], v[84:87], v[48:63]
	ds_read_b128 v[84:87], v131 offset:59968
	v_mfma_f32_32x32x16_bf16 v[0:15], v[108:111], v[92:95], v[0:15]
	ds_read_b128 v[108:111], v131 offset:59936
	ds_read_b128 v[92:95], v131 offset:60000
	v_mfma_f32_32x32x16_bf16 v[32:47], v[72:75], v[64:67], v[32:47]
	v_mfma_f32_32x32x16_bf16 v[16:31], v[72:75], v[68:71], v[16:31]
	ds_read_b128 v[72:75], v128 offset:18432
	v_mfma_f32_32x32x16_bf16 v[48:63], v[76:79], v[64:67], v[48:63]
	ds_read_b128 v[64:67], v128 offset:23040
	v_mfma_f32_32x32x16_bf16 v[0:15], v[76:79], v[68:71], v[0:15]
	ds_read_b128 v[76:79], v131 offset:55296
	ds_read_b128 v[68:71], v131 offset:59904
	s_waitcnt lgkmcnt(1)
	v_mfma_f32_32x32x16_bf16 v[32:47], v[76:79], v[72:75], v[32:47]
	s_waitcnt lgkmcnt(0)
	v_mfma_f32_32x32x16_bf16 v[48:63], v[68:71], v[72:75], v[48:63]
	ds_read_b128 v[72:75], v128 offset:18496
	v_mfma_f32_32x32x16_bf16 v[16:31], v[76:79], v[64:67], v[16:31]
	ds_read_b128 v[76:79], v128 offset:18528
	v_mfma_f32_32x32x16_bf16 v[0:15], v[68:71], v[64:67], v[0:15]
	ds_read_b128 v[64:67], v128 offset:23104
	ds_read_b128 v[68:71], v128 offset:23136
	s_waitcnt lgkmcnt(0)
	s_barrier
	v_mfma_f32_32x32x16_bf16 v[32:47], v[104:107], v[96:99], v[32:47]
	v_mfma_f32_32x32x16_bf16 v[16:31], v[104:107], v[100:103], v[16:31]
	v_mfma_f32_32x32x16_bf16 v[0:15], v[108:111], v[100:103], v[0:15]
	v_mfma_f32_32x32x16_bf16 v[32:47], v[80:83], v[72:75], v[32:47]
	v_mfma_f32_32x32x16_bf16 v[16:31], v[80:83], v[64:67], v[16:31]
	v_mfma_f32_32x32x16_bf16 v[0:15], v[84:87], v[64:67], v[0:15]
	v_mfma_f32_32x32x16_bf16 v[32:47], v[88:91], v[76:79], v[32:47]
	v_mfma_f32_32x32x16_bf16 v[48:63], v[108:111], v[96:99], v[48:63]
	v_mfma_f32_32x32x16_bf16 v[16:31], v[88:91], v[68:71], v[16:31]
	v_mfma_f32_32x32x16_bf16 v[0:15], v[92:95], v[68:71], v[0:15]
	v_mfma_f32_32x32x16_bf16 v[48:63], v[84:87], v[72:75], v[48:63]
	v_mfma_f32_32x32x16_bf16 v[48:63], v[92:95], v[76:79], v[48:63]
	v_and_b32_e32 v64, 63, v186
	v_lshrrev_b32_e32 v65, 6, v186
	v_and_b32_e32 v66, 31, v64
	v_lshrrev_b32_e32 v67, 5, v64
	v_lshrrev_b32_e32 v68, 1, v65
	v_and_b32_e32 v65, 1, v65
	v_lshl_add_u32 v66, v68, 6, v66
	v_mul_u32_u24_e32 v66, 0x1600, v66
	v_lshl_add_u32 v66, v65, 6, v66
	v_lshl_add_u32 v66, v67, 3, v66
	v_add_u32_e32 v67, 0x2c000, v66
	s_mul_i32 s8, s6, 0x1600
	s_lshl_b32 s9, s4, 7
	s_add_i32 s8, s8, s9
	s_add_u32 s10, s0, s8
	s_addc_u32 s11, s1, 0
	s_nop 7
	s_nop 3
	v_readfirstlane_b32 s20, v186
	v_and_b32_e32 v96, 31, v186
	v_bfe_u32 v99, v186, 5, 1
	s_lshr_b32 s20, s20, 6
	s_and_b32 s21, s20, 1
	s_lshr_b32 s22, s20, 1
	s_mul_i32 s26, s21, 0x1400
	s_mul_i32 s27, s22, 0x9000
	s_add_i32 s26, s26, s27
	v_mul_u32_u24_e32 v96, 0x50, v96
	v_lshl_add_u32 v96, v99, 3, v96
	v_add_u32_e32 v96, s26, v96
	v_and_b32_e32 v99, 63, v186
	v_lshrrev_b32_e32 v97, 2, v99
	v_and_b32_e32 v99, 3, v99
	v_mul_u32_u24_e32 v98, 0x1600, v97
	v_mul_u32_u24_e32 v97, 0x50, v97
	v_lshl_add_u32 v97, v99, 4, v97
	v_add_u32_e32 v97, s26, v97
	v_lshl_add_u32 v98, v99, 4, v98
	s_mul_i32 s27, s22, 0x58000
	s_lshl_b32 s26, s21, 6
	s_add_i32 s27, s27, s26
	v_add_u32_e32 v98, s27, v98
	s_waitcnt vmcnt(0)
	v_add_f32_e32 v222, v222, v223
	v_add_f32_e32 v224, v224, v225
	v_add_f32_e32 v226, v226, v227
	v_add_f32_e32 v228, v228, v229
	v_add_f32_e32 v222, v222, v224
	v_add_f32_e32 v226, v226, v228
	v_add_f32_e32 v222, v222, v226
	v_fmamk_f32 v250, v222, 0x3a800000, v187
	v_add_f32_e32 v136, v136, v137
	v_add_f32_e32 v138, v138, v139
	v_add_f32_e32 v140, v140, v141
	v_add_f32_e32 v142, v142, v143
	v_add_f32_e32 v136, v136, v138
	v_add_f32_e32 v140, v140, v142
	v_add_f32_e32 v136, v136, v140
	v_fmamk_f32 v249, v136, 0x3a800000, v187
	v_rsq_f32_e32 v250, v250
	v_rsq_f32_e32 v249, v249
	s_nop 0
	v_mul_f32_e32 v32, v250, v32
	v_mul_f32_e32 v33, v250, v33
	v_mul_f32_e32 v34, v250, v34
	v_mul_f32_e32 v35, v250, v35
	v_mul_f32_e32 v48, v250, v48
	v_mul_f32_e32 v49, v250, v49
	v_mul_f32_e32 v50, v250, v50
	v_mul_f32_e32 v51, v250, v51
	v_mul_f32_e32 v70, 0xbfb8aa3b, v32
	v_mul_f32_e32 v71, 0xbfb8aa3b, v33
	v_mul_f32_e32 v72, 0xbfb8aa3b, v34
	v_mul_f32_e32 v73, 0xbfb8aa3b, v35
	v_exp_f32_e32 v70, v70
	v_exp_f32_e32 v71, v71
	v_exp_f32_e32 v72, v72
	v_exp_f32_e32 v73, v73
	v_add_f32_e32 v70, 1.0, v70
	v_add_f32_e32 v71, 1.0, v71
	v_add_f32_e32 v72, 1.0, v72
	v_add_f32_e32 v73, 1.0, v73
	v_rcp_f32_e32 v70, v70
	v_rcp_f32_e32 v71, v71
	v_rcp_f32_e32 v72, v72
	v_rcp_f32_e32 v73, v73
	v_mul_f32_e32 v70, v32, v70
	v_mul_f32_e32 v71, v33, v71
	v_mul_f32_e32 v72, v34, v72
	v_mul_f32_e32 v73, v35, v73
	v_mul_f32_e32 v70, v48, v70
	v_mul_f32_e32 v71, v49, v71
	v_mul_f32_e32 v72, v50, v72
	v_mul_f32_e32 v73, v51, v73
	v_cvt_pk_bf16_f32 v74, v70, v71
	v_cvt_pk_bf16_f32 v75, v72, v73
	ds_write_b64 v96, v[74:75]
	v_mul_f32_e32 v36, v250, v36
	v_mul_f32_e32 v37, v250, v37
	v_mul_f32_e32 v38, v250, v38
	v_mul_f32_e32 v39, v250, v39
	v_mul_f32_e32 v52, v250, v52
	v_mul_f32_e32 v53, v250, v53
	v_mul_f32_e32 v54, v250, v54
	v_mul_f32_e32 v55, v250, v55
	v_mul_f32_e32 v76, 0xbfb8aa3b, v36
	v_mul_f32_e32 v77, 0xbfb8aa3b, v37
	v_mul_f32_e32 v78, 0xbfb8aa3b, v38
	v_mul_f32_e32 v79, 0xbfb8aa3b, v39
	v_exp_f32_e32 v76, v76
	v_exp_f32_e32 v77, v77
	v_exp_f32_e32 v78, v78
	v_exp_f32_e32 v79, v79
	v_add_f32_e32 v76, 1.0, v76
	v_add_f32_e32 v77, 1.0, v77
	v_add_f32_e32 v78, 1.0, v78
	v_add_f32_e32 v79, 1.0, v79
	v_rcp_f32_e32 v76, v76
	v_rcp_f32_e32 v77, v77
	v_rcp_f32_e32 v78, v78
	v_rcp_f32_e32 v79, v79
	v_mul_f32_e32 v76, v36, v76
	v_mul_f32_e32 v77, v37, v77
	v_mul_f32_e32 v78, v38, v78
	v_mul_f32_e32 v79, v39, v79
	v_mul_f32_e32 v76, v52, v76
	v_mul_f32_e32 v77, v53, v77
	v_mul_f32_e32 v78, v54, v78
	v_mul_f32_e32 v79, v55, v79
	v_cvt_pk_bf16_f32 v80, v76, v77
	v_cvt_pk_bf16_f32 v81, v78, v79
	ds_write_b64 v96, v[80:81] offset:16
	v_mul_f32_e32 v40, v250, v40
	v_mul_f32_e32 v41, v250, v41
	v_mul_f32_e32 v42, v250, v42
	v_mul_f32_e32 v43, v250, v43
	v_mul_f32_e32 v56, v250, v56
	v_mul_f32_e32 v57, v250, v57
	v_mul_f32_e32 v58, v250, v58
	v_mul_f32_e32 v59, v250, v59
	v_mul_f32_e32 v82, 0xbfb8aa3b, v40
	v_mul_f32_e32 v83, 0xbfb8aa3b, v41
	v_mul_f32_e32 v84, 0xbfb8aa3b, v42
	v_mul_f32_e32 v85, 0xbfb8aa3b, v43
	v_exp_f32_e32 v82, v82
	v_exp_f32_e32 v83, v83
	v_exp_f32_e32 v84, v84
	v_exp_f32_e32 v85, v85
	v_add_f32_e32 v82, 1.0, v82
	v_add_f32_e32 v83, 1.0, v83
	v_add_f32_e32 v84, 1.0, v84
	v_add_f32_e32 v85, 1.0, v85
	v_rcp_f32_e32 v82, v82
	v_rcp_f32_e32 v83, v83
	v_rcp_f32_e32 v84, v84
	v_rcp_f32_e32 v85, v85
	v_mul_f32_e32 v82, v40, v82
	v_mul_f32_e32 v83, v41, v83
	v_mul_f32_e32 v84, v42, v84
	v_mul_f32_e32 v85, v43, v85
	v_mul_f32_e32 v82, v56, v82
	v_mul_f32_e32 v83, v57, v83
	v_mul_f32_e32 v84, v58, v84
	v_mul_f32_e32 v85, v59, v85
	v_cvt_pk_bf16_f32 v86, v82, v83
	v_cvt_pk_bf16_f32 v87, v84, v85
	ds_write_b64 v96, v[86:87] offset:32
	v_mul_f32_e32 v44, v250, v44
	v_mul_f32_e32 v45, v250, v45
	v_mul_f32_e32 v46, v250, v46
	v_mul_f32_e32 v47, v250, v47
	v_mul_f32_e32 v60, v250, v60
	v_mul_f32_e32 v61, v250, v61
	v_mul_f32_e32 v62, v250, v62
	v_mul_f32_e32 v63, v250, v63
	v_mul_f32_e32 v70, 0xbfb8aa3b, v44
	v_mul_f32_e32 v71, 0xbfb8aa3b, v45
	v_mul_f32_e32 v72, 0xbfb8aa3b, v46
	v_mul_f32_e32 v73, 0xbfb8aa3b, v47
	v_exp_f32_e32 v70, v70
	v_exp_f32_e32 v71, v71
	v_exp_f32_e32 v72, v72
	v_exp_f32_e32 v73, v73
	v_add_f32_e32 v70, 1.0, v70
	v_add_f32_e32 v71, 1.0, v71
	v_add_f32_e32 v72, 1.0, v72
	v_add_f32_e32 v73, 1.0, v73
	v_rcp_f32_e32 v70, v70
	v_rcp_f32_e32 v71, v71
	v_rcp_f32_e32 v72, v72
	v_rcp_f32_e32 v73, v73
	v_mul_f32_e32 v70, v44, v70
	v_mul_f32_e32 v71, v45, v71
	v_mul_f32_e32 v72, v46, v72
	v_mul_f32_e32 v73, v47, v73
	v_mul_f32_e32 v70, v60, v70
	v_mul_f32_e32 v71, v61, v71
	v_mul_f32_e32 v72, v62, v72
	v_mul_f32_e32 v73, v63, v73
	v_cvt_pk_bf16_f32 v74, v70, v71
	v_cvt_pk_bf16_f32 v75, v72, v73
	ds_write_b64 v96, v[74:75] offset:48
	v_mul_f32_e32 v16, v249, v16
	v_mul_f32_e32 v17, v249, v17
	v_mul_f32_e32 v18, v249, v18
	v_mul_f32_e32 v19, v249, v19
	v_mul_f32_e32 v0, v249, v0
	v_mul_f32_e32 v1, v249, v1
	v_mul_f32_e32 v2, v249, v2
	v_mul_f32_e32 v3, v249, v3
	v_mul_f32_e32 v76, 0xbfb8aa3b, v16
	v_mul_f32_e32 v77, 0xbfb8aa3b, v17
	v_mul_f32_e32 v78, 0xbfb8aa3b, v18
	v_mul_f32_e32 v79, 0xbfb8aa3b, v19
	v_exp_f32_e32 v76, v76
	v_exp_f32_e32 v77, v77
	v_exp_f32_e32 v78, v78
	v_exp_f32_e32 v79, v79
	v_add_f32_e32 v76, 1.0, v76
	v_add_f32_e32 v77, 1.0, v77
	v_add_f32_e32 v78, 1.0, v78
	v_add_f32_e32 v79, 1.0, v79
	v_rcp_f32_e32 v76, v76
	v_rcp_f32_e32 v77, v77
	v_rcp_f32_e32 v78, v78
	v_rcp_f32_e32 v79, v79
	v_mul_f32_e32 v76, v16, v76
	v_mul_f32_e32 v77, v17, v77
	v_mul_f32_e32 v78, v18, v78
	v_mul_f32_e32 v79, v19, v79
	v_mul_f32_e32 v76, v0, v76
	v_mul_f32_e32 v77, v1, v77
	v_mul_f32_e32 v78, v2, v78
	v_mul_f32_e32 v79, v3, v79
	v_cvt_pk_bf16_f32 v80, v76, v77
	v_cvt_pk_bf16_f32 v81, v78, v79
	ds_write_b64 v96, v[80:81] offset:2560
	v_mul_f32_e32 v20, v249, v20
	v_mul_f32_e32 v21, v249, v21
	v_mul_f32_e32 v22, v249, v22
	v_mul_f32_e32 v23, v249, v23
	v_mul_f32_e32 v4, v249, v4
	v_mul_f32_e32 v5, v249, v5
	v_mul_f32_e32 v6, v249, v6
	v_mul_f32_e32 v7, v249, v7
	v_mul_f32_e32 v82, 0xbfb8aa3b, v20
	v_mul_f32_e32 v83, 0xbfb8aa3b, v21
	v_mul_f32_e32 v84, 0xbfb8aa3b, v22
	v_mul_f32_e32 v85, 0xbfb8aa3b, v23
	v_exp_f32_e32 v82, v82
	v_exp_f32_e32 v83, v83
	v_exp_f32_e32 v84, v84
	v_exp_f32_e32 v85, v85
	v_add_f32_e32 v82, 1.0, v82
	v_add_f32_e32 v83, 1.0, v83
	v_add_f32_e32 v84, 1.0, v84
	v_add_f32_e32 v85, 1.0, v85
	v_rcp_f32_e32 v82, v82
	v_rcp_f32_e32 v83, v83
	v_rcp_f32_e32 v84, v84
	v_rcp_f32_e32 v85, v85
	v_mul_f32_e32 v82, v20, v82
	v_mul_f32_e32 v83, v21, v83
	v_mul_f32_e32 v84, v22, v84
	v_mul_f32_e32 v85, v23, v85
	v_mul_f32_e32 v82, v4, v82
	v_mul_f32_e32 v83, v5, v83
	v_mul_f32_e32 v84, v6, v84
	v_mul_f32_e32 v85, v7, v85
	v_cvt_pk_bf16_f32 v86, v82, v83
	v_cvt_pk_bf16_f32 v87, v84, v85
	ds_write_b64 v96, v[86:87] offset:2576
	v_mul_f32_e32 v24, v249, v24
	v_mul_f32_e32 v25, v249, v25
	v_mul_f32_e32 v26, v249, v26
	v_mul_f32_e32 v27, v249, v27
	v_mul_f32_e32 v8, v249, v8
	v_mul_f32_e32 v9, v249, v9
	v_mul_f32_e32 v10, v249, v10
	v_mul_f32_e32 v11, v249, v11
	v_mul_f32_e32 v70, 0xbfb8aa3b, v24
	v_mul_f32_e32 v71, 0xbfb8aa3b, v25
	v_mul_f32_e32 v72, 0xbfb8aa3b, v26
	v_mul_f32_e32 v73, 0xbfb8aa3b, v27
	v_exp_f32_e32 v70, v70
	v_exp_f32_e32 v71, v71
	v_exp_f32_e32 v72, v72
	v_exp_f32_e32 v73, v73
	v_add_f32_e32 v70, 1.0, v70
	v_add_f32_e32 v71, 1.0, v71
	v_add_f32_e32 v72, 1.0, v72
	v_add_f32_e32 v73, 1.0, v73
	v_rcp_f32_e32 v70, v70
	v_rcp_f32_e32 v71, v71
	v_rcp_f32_e32 v72, v72
	v_rcp_f32_e32 v73, v73
	v_mul_f32_e32 v70, v24, v70
	v_mul_f32_e32 v71, v25, v71
	v_mul_f32_e32 v72, v26, v72
	v_mul_f32_e32 v73, v27, v73
	v_mul_f32_e32 v70, v8, v70
	v_mul_f32_e32 v71, v9, v71
	v_mul_f32_e32 v72, v10, v72
	v_mul_f32_e32 v73, v11, v73
	v_cvt_pk_bf16_f32 v74, v70, v71
	v_cvt_pk_bf16_f32 v75, v72, v73
	ds_write_b64 v96, v[74:75] offset:2592
	v_mul_f32_e32 v28, v249, v28
	v_mul_f32_e32 v29, v249, v29
	v_mul_f32_e32 v30, v249, v30
	v_mul_f32_e32 v31, v249, v31
	v_mul_f32_e32 v12, v249, v12
	v_mul_f32_e32 v13, v249, v13
	v_mul_f32_e32 v14, v249, v14
	v_mul_f32_e32 v15, v249, v15
	v_mul_f32_e32 v76, 0xbfb8aa3b, v28
	v_mul_f32_e32 v77, 0xbfb8aa3b, v29
	v_mul_f32_e32 v78, 0xbfb8aa3b, v30
	v_mul_f32_e32 v79, 0xbfb8aa3b, v31
	v_exp_f32_e32 v76, v76
	v_exp_f32_e32 v77, v77
	v_exp_f32_e32 v78, v78
	v_exp_f32_e32 v79, v79
	v_add_f32_e32 v76, 1.0, v76
	v_add_f32_e32 v77, 1.0, v77
	v_add_f32_e32 v78, 1.0, v78
	v_add_f32_e32 v79, 1.0, v79
	v_rcp_f32_e32 v76, v76
	v_rcp_f32_e32 v77, v77
	v_rcp_f32_e32 v78, v78
	v_rcp_f32_e32 v79, v79
	v_mul_f32_e32 v76, v28, v76
	v_mul_f32_e32 v77, v29, v77
	v_mul_f32_e32 v78, v30, v78
	v_mul_f32_e32 v79, v31, v79
	v_mul_f32_e32 v76, v12, v76
	v_mul_f32_e32 v77, v13, v77
	v_mul_f32_e32 v78, v14, v78
	v_mul_f32_e32 v79, v15, v79
	v_cvt_pk_bf16_f32 v80, v76, v77
	v_cvt_pk_bf16_f32 v81, v78, v79
	ds_write_b64 v96, v[80:81] offset:2608
	s_waitcnt lgkmcnt(0)
	ds_read_b128 v[100:103], v97
	ds_read_b128 v[104:107], v97 offset:1280
	ds_read_b128 v[108:111], v97 offset:2560
	ds_read_b128 v[112:115], v97 offset:3840
	s_waitcnt lgkmcnt(3)
	global_store_dwordx4 v98, v[100:103], s[10:11]
	s_add_u32 s10, s10, 0x16000
	s_addc_u32 s11, s11, 0
	s_waitcnt lgkmcnt(2)
	global_store_dwordx4 v98, v[104:107], s[10:11]
	s_add_u32 s10, s10, 0x16000
	s_addc_u32 s11, s11, 0
	s_waitcnt lgkmcnt(1)
	global_store_dwordx4 v98, v[108:111], s[10:11]
	s_add_u32 s10, s10, 0x16000
	s_addc_u32 s11, s11, 0
	s_waitcnt lgkmcnt(0)
	global_store_dwordx4 v98, v[112:115], s[10:11]
	v_readlane_b32 s4, v252, 22
	s_add_i32 s16, s16, s4
	s_cmp_ge_i32 s16, s23
	s_cbranch_scc1 .LBB0_2270
